# 64-byte alignment (.p2align 6) of the four GEMM K-loop heads and their first-iteration copies
# speedup vs baseline: 1.0117x; 1.0117x over previous
; template <class Epi, bool ALIGN_EPI = PG8_ALIGN, bool SP2 = PG8_SP2>
; __device__ __forceinline__ void gemm_phase(LAS unsigned char* lds, const Gemm g, const StaticOrder& S, const Epi& E) {
;     ...
;         const bool has_next = S.next(ui + 1, nxt);
;         const char* nA = has_next ? (const char*)g.A + (size_t)nxt.pm * tstepA : cA; const char* nB = has_next ? (const char*)g.Bt + (size_t)nxt.pn * tstepB : cB;
;         for (int t = 0; t < nt; t += 2) {
;             const bool last = (t == nt - 2);
;             const char* a1 = cA + (size_t)(t + 1) * kstepA;
;             const char* a2 = last ? nA : cA + (size_t)(t + 2) * kstepA; const char* b2 = last ? nB : cB + (size_t)(t + 2) * kstepB;
;             const char* a3 = a2 + kstepA; const char* b3 = b2 + kstepB;
.LBB0_138:
	s_ashr_i32 s17, s16, 31
	s_lshl_b64 s[18:19], s[16:17], 19
	v_readlane_b32 s20, v252, 58
	v_readlane_b32 s21, v252, 59
	s_add_u32 s18, s20, s18
	s_addc_u32 s19, s21, s19
	s_and_b64 s[20:21], s[6:7], exec
	s_cselect_b32 s17, s19, s5
	s_cselect_b32 s36, s18, s4
	s_ashr_i32 s15, s14, 31
	s_lshl_b64 s[20:21], s[14:15], 19
	v_readlane_b32 s24, v252, 9
	v_readlane_b32 s25, v252, 10
	s_add_u32 s20, s24, s20
	s_addc_u32 s21, s25, s21
	s_and_b64 s[24:25], s[6:7], exec
	s_cselect_b32 s15, s21, s23
	s_cselect_b32 s37, s20, s22
	s_add_u32 s4, s4, 0x40080
	s_addc_u32 s5, s5, 0
	s_add_u32 s38, s22, 0x100
	s_addc_u32 s39, s23, 0
	s_mov_b32 s40, -2
	.p2align 6

; #define PG8_BAR __builtin_amdgcn_s_barrier()
; template <class Epi, bool ALIGN_EPI = PG8_ALIGN, bool SP2 = PG8_SP2>
; __device__ __forceinline__ void gemm_phase(LAS unsigned char* lds, const Gemm g, const StaticOrder& S, const Epi& E) {
;     ...
;         if constexpr (ALIGN_EPI) { if (wr == 0) PG8_BAR; }
;         E(acc, cur, wr, wc, fr, fq);
;         if (!has_next) break;
; #pragma unroll
;         for (int a = 0; a < 2; ++a)
; #pragma unroll
;             for (int b = 0; b < 2; ++b)
; #pragma unroll
;                 for (int m = 0; m < 4; ++m)
; #pragma unroll
;                     for (int n = 0; n < 2; ++n) acc[a][b][m][n] = (f32x4){0.f, 0.f, 0.f, 0.f};
;         cur = nxt; cA = nA; cB = nB; ++ui;
;         if constexpr (ALIGN_EPI) { if (wr == 1) PG8_BAR; }
.LBB0_174:
	s_andn2_b64 vcc, exec, s[6:7]
	s_mov_b64 s[4:5], -1
	s_cbranch_vccnz .LBB0_131
	s_andn2_b64 vcc, exec, s[10:11]
	s_cbranch_vccnz .LBB0_130
	s_barrier
	s_branch .LBB0_130
	.p2align 6

; template <class Epi, bool ALIGN_EPI = PG8_ALIGN, bool SP2 = PG8_SP2>
; __device__ __forceinline__ void gemm_phase(LAS unsigned char* lds, const Gemm g, const StaticOrder& S, const Epi& E) {
;     ...
;         const bool has_next = S.next(ui + 1, nxt);
;         const char* nA = has_next ? (const char*)g.A + (size_t)nxt.pm * tstepA : cA; const char* nB = has_next ? (const char*)g.Bt + (size_t)nxt.pn * tstepB : cB;
;         for (int t = 0; t < nt; t += 2) {
;             const bool last = (t == nt - 2);
;             const char* a1 = cA + (size_t)(t + 1) * kstepA;
;             const char* a2 = last ? nA : cA + (size_t)(t + 2) * kstepA; const char* b2 = last ? nB : cB + (size_t)(t + 2) * kstepB;
;             const char* a3 = a2 + kstepA; const char* b3 = b2 + kstepB;
.LBB0_534:
	s_ashr_i32 s19, s18, 31
	s_lshl_b64 s[8:9], s[18:19], 19
	v_readlane_b32 s20, v252, 58
	v_readlane_b32 s21, v252, 59
	s_add_u32 s20, s20, s8
	s_addc_u32 s21, s21, s9
	s_and_b64 s[8:9], s[6:7], exec
	s_cselect_b32 s19, s21, s1
	s_cselect_b32 s35, s20, s0
	s_ashr_i32 s17, s16, 31
	s_lshl_b64 s[8:9], s[16:17], 19
	v_readlane_b32 s22, v252, 54
	v_readlane_b32 s23, v252, 55
	s_add_u32 s22, s22, s8
	s_addc_u32 s23, s23, s9
	s_and_b64 s[8:9], s[6:7], exec
	s_cselect_b32 s17, s23, s5
	s_cselect_b32 s36, s22, s4
	s_add_u32 s0, s0, 0x40080
	s_addc_u32 s1, s1, 0
	s_add_u32 s37, s4, 0x100
	s_addc_u32 s38, s5, 0
	s_mov_b32 s39, -2
	.p2align 6

; #define PG8_BAR __builtin_amdgcn_s_barrier()
; template <class Epi, bool ALIGN_EPI = PG8_ALIGN, bool SP2 = PG8_SP2>
; __device__ __forceinline__ void gemm_phase(LAS unsigned char* lds, const Gemm g, const StaticOrder& S, const Epi& E) {
;     ...
;         if (!has_next) break;
; #pragma unroll
;         for (int a = 0; a < 2; ++a)
; #pragma unroll
;             for (int b = 0; b < 2; ++b)
; #pragma unroll
;                 for (int m = 0; m < 4; ++m)
; #pragma unroll
;                     for (int n = 0; n < 2; ++n) acc[a][b][m][n] = (f32x4){0.f, 0.f, 0.f, 0.f};
;         cur = nxt; cA = nA; cB = nB; ++ui;
;         if constexpr (ALIGN_EPI) { if (wr == 1) PG8_BAR; }
.LBB0_544:
	s_andn2_b64 vcc, exec, s[6:7]
	s_mov_b64 s[0:1], -1
	s_cbranch_vccnz .LBB0_527
	s_branch .LBB0_549
	.p2align 6

; template <class Epi, bool ALIGN_EPI = PG8_ALIGN, bool SP2 = PG8_SP2>
; __device__ __forceinline__ void gemm_phase(LAS unsigned char* lds, const Gemm g, const StaticOrder& S, const Epi& E) {
;     ...
;         const bool has_next = S.next(ui + 1, nxt);
;         const char* nA = has_next ? (const char*)g.A + (size_t)nxt.pm * tstepA : cA; const char* nB = has_next ? (const char*)g.Bt + (size_t)nxt.pn * tstepB : cB;
;         for (int t = 0; t < nt; t += 2) {
;             const bool last = (t == nt - 2);
;             const char* a1 = cA + (size_t)(t + 1) * kstepA;
;             const char* a2 = last ? nA : cA + (size_t)(t + 2) * kstepA; const char* b2 = last ? nB : cB + (size_t)(t + 2) * kstepB;
;             const char* a3 = a2 + kstepA; const char* b3 = b2 + kstepB;
.LBB0_582:
	s_add_u32 s71, s26, s38
	s_addc_u32 s72, s27, s33
	s_mov_b64 s[28:29], 0
	.p2align 6

;     __device__ __forceinline__ void operator()(const f32x4 (&acc)[2][2][4][2], const pg8::Unit& u, int wr, int wc, int fr, int fq) const {
;         const int row0 = u.pm * 256 + wr * 64 + fr, col0 = u.pn * 256 + wc * 32 + 8 * fq;
;         const bool isctx = u.pm >= T / 256; const int mb = isctx ? 2 : (u.pm >> 6);
;         const float* xi = isctx ? xin_ctx - (size_t)T * D : xin_lat; float* xo = isctx ? xout_ctx - (size_t)T * D : xout_lat;
;         const float* gp = gate + mb * 9216 + col0;
;         f32x4 gv[2][2];
; #pragma unroll
;         for (int bj = 0; bj < 2; ++bj)
; #pragma unroll
;             for (int n = 0; n < 2; ++n) gv[bj][n] = *(const f32x4*)(gp + bj * 128 + n * 4) * coef;
; #pragma unroll
;         for (int ai = 0; ai < 2; ++ai) {
;             f32x4 xv[4][2][2];
; #pragma unroll
;             for (int m = 0; m < 4; ++m)
; #pragma unroll
;                 for (int bj = 0; bj < 2; ++bj)
; #pragma unroll
;                     for (int n = 0; n < 2; ++n) xv[m][bj][n] = *(const f32x4*)(xi + (size_t)(row0 + ai * 128 + m * 16) * D + col0 + bj * 128 + n * 4);
; #pragma unroll
;             for (int m = 0; m < 4; ++m)
; #pragma unroll
;                 for (int bj = 0; bj < 2; ++bj)
; #pragma unroll
;                     for (int n = 0; n < 2; ++n) *(f32x4*)(xo + (size_t)(row0 + ai * 128 + m * 16) * D + col0 + bj * 128 + n * 4) = xv[m][bj][n] + gv[bj][n] * acc[ai][bj][m][n];
.LBB0_586:
	s_lshr_b32 s24, s69, 6
	s_cmpk_gt_i32 s69, 0x7f
	s_mulk_i32 s24, 0x2400
	v_readlane_b32 s25, v250, 46
	s_cselect_b32 s24, 0x4800, s24
	s_cselect_b32 s28, s25, s90
	v_readlane_b32 s25, v250, 47
	s_cselect_b32 s26, s62, s46
	s_cselect_b32 s27, s63, s45
	s_cselect_b32 s29, s25, s91
	s_ashr_i32 s25, s24, 31
	v_lshl_or_b32 v132, s70, 8, v156
	s_lshl_b64 s[24:25], s[24:25], 2
	s_add_u32 s24, s47, s24
	v_ashrrev_i32_e32 v133, 31, v132
	s_addc_u32 s25, s48, s25
	v_lshlrev_b64 v[132:133], 2, v[132:133]
	v_lshl_add_u64 v[142:143], s[24:25], 0, v[132:133]
	global_load_dwordx4 v[134:137], v[142:143], off offset:16
	global_load_dwordx4 v[138:141], v[142:143], off
	global_load_dwordx4 v[158:161], v[142:143], off offset:528
	global_load_dwordx4 v[170:173], v[142:143], off offset:512
	v_lshl_add_u32 v142, s69, 8, v154
	v_ashrrev_i32_e32 v143, 31, v142
	v_lshl_add_u64 v[150:151], s[26:27], 0, v[132:133]
	v_lshlrev_b64 v[152:153], 12, v[142:143]
	v_lshl_add_u64 v[144:145], v[150:151], 0, v[152:153]
	global_load_dwordx4 v[174:177], v[144:145], off
	global_load_dwordx4 v[178:181], v[144:145], off offset:16
	global_load_dwordx4 v[182:185], v[144:145], off offset:528
	global_load_dwordx4 v[186:189], v[144:145], off offset:512
	v_or_b32_e32 v144, 16, v142
	v_ashrrev_i32_e32 v145, 31, v144
	v_lshlrev_b64 v[144:145], 12, v[144:145]
	v_lshl_add_u64 v[146:147], v[150:151], 0, v[144:145]
	global_load_dwordx4 v[206:209], v[146:147], off
	global_load_dwordx4 v[210:213], v[146:147], off offset:16
	global_load_dwordx4 v[214:217], v[146:147], off offset:528
	global_load_dwordx4 v[218:221], v[146:147], off offset:512
	v_or_b32_e32 v146, 32, v142
	v_ashrrev_i32_e32 v147, 31, v146
	v_lshlrev_b64 v[146:147], 12, v[146:147]
	v_or_b32_e32 v142, 48, v142
	v_lshl_add_u64 v[148:149], v[150:151], 0, v[146:147]
	v_ashrrev_i32_e32 v143, 31, v142
	global_load_dwordx4 v[222:225], v[148:149], off
	global_load_dwordx4 v[226:229], v[148:149], off offset:16
	global_load_dwordx4 v[230:233], v[148:149], off offset:512
	global_load_dwordx4 v[234:237], v[148:149], off offset:528
	v_lshlrev_b64 v[202:203], 12, v[142:143]
	v_lshl_add_u64 v[142:143], v[150:151], 0, v[202:203]
	global_load_dwordx4 v[238:241], v[142:143], off
	global_load_dwordx4 v[242:245], v[142:143], off offset:16
	global_load_dwordx4 v[194:197], v[142:143], off offset:512
	global_load_dwordx4 v[164:167], v[142:143], off offset:528
	v_lshl_add_u64 v[132:133], s[28:29], 0, v[132:133]
	v_lshl_add_u64 v[190:191], v[132:133], 0, v[144:145]
	v_lshl_add_u64 v[204:205], v[132:133], 0, v[146:147]
	s_mov_b64 s[24:25], 0x80000
	v_lshl_add_u64 v[246:247], v[132:133], 0, v[152:153]
	s_and_b64 vcc, exec, s[4:5]
	s_mov_b64 s[4:5], -1
	s_waitcnt vmcnt(0)
	v_pk_mul_f32 v[142:143], s[16:17], v[136:137]
	v_pk_mul_f32 v[146:147], s[16:17], v[140:141]
	v_pk_mul_f32 v[148:149], s[12:13], v[138:139]
	v_pk_mul_f32 v[144:145], s[12:13], v[134:135]
	v_pk_mul_f32 v[138:139], s[16:17], v[172:173]
	v_pk_mul_f32 v[140:141], s[12:13], v[170:171]
	v_pk_mul_f32 v[134:135], s[16:17], v[160:161]
	v_pk_mul_f32 v[136:137], s[12:13], v[158:159]
	v_pk_fma_f32 v[128:129], v[128:129], v[146:147], v[176:177]
	v_pk_fma_f32 v[126:127], v[126:127], v[148:149], v[174:175]
	v_lshl_add_u64 v[158:159], v[152:153], 0, s[24:25]
	s_mov_b64 s[24:25], 0x90000
	v_pk_fma_f32 v[124:125], v[124:125], v[142:143], v[180:181]
	v_pk_fma_f32 v[122:123], v[122:123], v[144:145], v[178:179]
	v_pk_fma_f32 v[108:109], v[108:109], v[138:139], v[188:189]
	v_pk_fma_f32 v[106:107], v[106:107], v[140:141], v[186:187]
	v_pk_fma_f32 v[104:105], v[104:105], v[134:135], v[184:185]
	v_pk_fma_f32 v[102:103], v[102:103], v[136:137], v[182:183]
	v_pk_fma_f32 v[120:121], v[120:121], v[146:147], v[208:209]
	v_pk_fma_f32 v[118:119], v[118:119], v[148:149], v[206:207]
	v_pk_fma_f32 v[116:117], v[116:117], v[142:143], v[212:213]
	v_pk_fma_f32 v[84:85], v[84:85], v[138:139], v[232:233]
	v_pk_fma_f32 v[82:83], v[82:83], v[140:141], v[230:231]
	v_pk_fma_f32 v[76:77], v[76:77], v[134:135], v[236:237]
	v_pk_fma_f32 v[74:75], v[74:75], v[136:137], v[234:235]
	v_pk_fma_f32 v[114:115], v[114:115], v[144:145], v[210:211]
	v_pk_fma_f32 v[100:101], v[100:101], v[138:139], v[220:221]
	v_pk_fma_f32 v[98:99], v[98:99], v[140:141], v[218:219]
	v_pk_fma_f32 v[96:97], v[96:97], v[134:135], v[216:217]
	v_pk_fma_f32 v[94:95], v[94:95], v[136:137], v[214:215]
	v_pk_fma_f32 v[112:113], v[112:113], v[146:147], v[224:225]
	v_pk_fma_f32 v[110:111], v[110:111], v[148:149], v[222:223]
	global_store_dwordx4 v[246:247], v[126:129], off
	global_store_dwordx4 v[246:247], v[122:125], off offset:16
	global_store_dwordx4 v[246:247], v[106:109], off offset:512
	global_store_dwordx4 v[246:247], v[102:105], off offset:528
	global_store_dwordx4 v[190:191], v[118:121], off
	global_store_dwordx4 v[190:191], v[114:117], off offset:16
	global_store_dwordx4 v[190:191], v[98:101], off offset:512
	global_store_dwordx4 v[190:191], v[94:97], off offset:528
	global_store_dwordx4 v[204:205], v[110:113], off
	global_store_dwordx4 v[204:205], v[82:85], off offset:512
	global_store_dwordx4 v[204:205], v[74:77], off offset:528
	v_lshl_add_u64 v[160:161], v[152:153], 0, s[24:25]
	v_lshl_add_u64 v[82:83], v[132:133], 0, v[202:203]
	v_pk_fma_f32 v[76:77], v[88:89], v[146:147], v[240:241]
; #define PG8_BAR __builtin_amdgcn_s_barrier()
; template <class Epi, bool ALIGN_EPI = PG8_ALIGN, bool SP2 = PG8_SP2>
; __device__ __forceinline__ void gemm_phase(LAS unsigned char* lds, const Gemm g, const StaticOrder& S, const Epi& E) {
;     ...
;         if (!has_next) break;
; #pragma unroll
;         for (int a = 0; a < 2; ++a)
; #pragma unroll
;             for (int b = 0; b < 2; ++b)
; #pragma unroll
;                 for (int m = 0; m < 4; ++m)
; #pragma unroll
;                     for (int n = 0; n < 2; ++n) acc[a][b][m][n] = (f32x4){0.f, 0.f, 0.f, 0.f};
;         cur = nxt; cA = nA; cB = nB; ++ui;
;         if constexpr (ALIGN_EPI) { if (wr == 1) PG8_BAR; }
;     __device__ __forceinline__ void operator()(const f32x4 (&acc)[2][2][4][2], const pg8::Unit& u, int wr, int wc, int fr, int fq) const {
;     ...
;         for (int ai = 0; ai < 2; ++ai) {
;             f32x4 xv[4][2][2];
; #pragma unroll
;             for (int m = 0; m < 4; ++m)
; #pragma unroll
;                 for (int bj = 0; bj < 2; ++bj)
; #pragma unroll
;                     for (int n = 0; n < 2; ++n) xv[m][bj][n] = *(const f32x4*)(xi + (size_t)(row0 + ai * 128 + m * 16) * D + col0 + bj * 128 + n * 4);
; #pragma unroll
;             for (int m = 0; m < 4; ++m)
; #pragma unroll
;                 for (int bj = 0; bj < 2; ++bj)
; #pragma unroll
;                     for (int n = 0; n < 2; ++n) *(f32x4*)(xo + (size_t)(row0 + ai * 128 + m * 16) * D + col0 + bj * 128 + n * 4) = xv[m][bj][n] + gv[bj][n] * acc[ai][bj][m][n];
	v_pk_fma_f32 v[74:75], v[86:87], v[148:149], v[238:239]
	s_mov_b64 s[24:25], 0xa0000
	v_pk_fma_f32 v[92:93], v[92:93], v[142:143], v[228:229]
	v_pk_fma_f32 v[90:91], v[90:91], v[144:145], v[226:227]
	global_store_dwordx4 v[82:83], v[74:77], off
	v_pk_fma_f32 v[72:73], v[72:73], v[138:139], v[196:197]
	v_pk_fma_f32 v[70:71], v[70:71], v[140:141], v[194:195]
	v_pk_fma_f32 v[76:77], v[80:81], v[142:143], v[244:245]
	v_pk_fma_f32 v[74:75], v[78:79], v[144:145], v[242:243]
	v_pk_fma_f32 v[68:69], v[68:69], v[134:135], v[166:167]
	v_pk_fma_f32 v[66:67], v[66:67], v[136:137], v[164:165]
	v_lshl_add_u64 v[164:165], v[152:153], 0, s[24:25]
	global_store_dwordx4 v[204:205], v[90:93], off offset:16
	global_store_dwordx4 v[82:83], v[74:77], off offset:16
	global_store_dwordx4 v[82:83], v[70:73], off offset:512
	global_store_dwordx4 v[82:83], v[66:69], off offset:528
	v_lshl_add_u64 v[78:79], v[150:151], 0, v[158:159]
	v_lshl_add_u64 v[94:95], v[150:151], 0, v[160:161]
	v_lshl_add_u64 v[110:111], v[150:151], 0, v[164:165]
	s_mov_b64 s[24:25], 0xb0000
	global_load_dwordx4 v[66:69], v[78:79], off
	global_load_dwordx4 v[70:73], v[78:79], off offset:16
	global_load_dwordx4 v[74:77], v[78:79], off offset:512
	s_nop 0
	global_load_dwordx4 v[78:81], v[78:79], off offset:528
	s_nop 0
	global_load_dwordx4 v[82:85], v[94:95], off
	global_load_dwordx4 v[86:89], v[94:95], off offset:16
	global_load_dwordx4 v[90:93], v[94:95], off offset:512
	s_nop 0
	global_load_dwordx4 v[94:97], v[94:95], off offset:528
	s_nop 0
	global_load_dwordx4 v[98:101], v[110:111], off
	global_load_dwordx4 v[102:105], v[110:111], off offset:16
	global_load_dwordx4 v[106:109], v[110:111], off offset:512
	s_nop 0
	global_load_dwordx4 v[110:113], v[110:111], off offset:528
	v_lshl_add_u64 v[152:153], v[152:153], 0, s[24:25]
	v_lshl_add_u64 v[126:127], v[150:151], 0, v[152:153]
	global_load_dwordx4 v[114:117], v[126:127], off
	global_load_dwordx4 v[118:121], v[126:127], off offset:16
	global_load_dwordx4 v[122:125], v[126:127], off offset:512
	s_nop 0
	global_load_dwordx4 v[126:129], v[126:127], off offset:528
	v_lshl_add_u64 v[150:151], v[132:133], 0, v[158:159]
	v_lshl_add_u64 v[158:159], v[132:133], 0, v[160:161]
	v_lshl_add_u64 v[160:161], v[132:133], 0, v[164:165]
	s_waitcnt vmcnt(15)
	v_pk_fma_f32 v[64:65], v[64:65], v[146:147], v[68:69]
	v_pk_fma_f32 v[62:63], v[62:63], v[148:149], v[66:67]
	s_waitcnt vmcnt(14)
	v_pk_fma_f32 v[60:61], v[60:61], v[142:143], v[72:73]
	v_pk_fma_f32 v[58:59], v[58:59], v[144:145], v[70:71]
	s_waitcnt vmcnt(5)
	v_pk_fma_f32 v[22:23], v[22:23], v[140:141], v[106:107]
	s_waitcnt vmcnt(4)
	v_pk_fma_f32 v[12:13], v[12:13], v[134:135], v[112:113]
	v_pk_fma_f32 v[10:11], v[10:11], v[136:137], v[110:111]
	v_pk_fma_f32 v[44:45], v[44:45], v[138:139], v[76:77]
	v_pk_fma_f32 v[42:43], v[42:43], v[140:141], v[74:75]
	v_pk_fma_f32 v[40:41], v[40:41], v[134:135], v[80:81]
	v_pk_fma_f32 v[38:39], v[38:39], v[136:137], v[78:79]
	v_pk_fma_f32 v[56:57], v[56:57], v[146:147], v[84:85]
	v_pk_fma_f32 v[54:55], v[54:55], v[148:149], v[82:83]
	v_pk_fma_f32 v[52:53], v[52:53], v[142:143], v[88:89]
	v_pk_fma_f32 v[50:51], v[50:51], v[144:145], v[86:87]
	v_pk_fma_f32 v[32:33], v[32:33], v[138:139], v[92:93]
	v_pk_fma_f32 v[30:31], v[30:31], v[140:141], v[90:91]
	v_pk_fma_f32 v[28:29], v[28:29], v[134:135], v[96:97]
	v_pk_fma_f32 v[26:27], v[26:27], v[136:137], v[94:95]
	v_pk_fma_f32 v[48:49], v[48:49], v[146:147], v[100:101]
	v_pk_fma_f32 v[46:47], v[46:47], v[148:149], v[98:99]
	v_pk_fma_f32 v[36:37], v[36:37], v[142:143], v[104:105]
	v_pk_fma_f32 v[34:35], v[34:35], v[144:145], v[102:103]
	v_pk_fma_f32 v[24:25], v[24:25], v[138:139], v[108:109]
	global_store_dwordx4 v[150:151], v[62:65], off
	global_store_dwordx4 v[150:151], v[58:61], off offset:16
	global_store_dwordx4 v[150:151], v[42:45], off offset:512
	global_store_dwordx4 v[150:151], v[38:41], off offset:528
	global_store_dwordx4 v[158:159], v[54:57], off
	global_store_dwordx4 v[158:159], v[50:53], off offset:16
	global_store_dwordx4 v[158:159], v[30:33], off offset:512
	global_store_dwordx4 v[158:159], v[26:29], off offset:528
	global_store_dwordx4 v[160:161], v[46:49], off
	global_store_dwordx4 v[160:161], v[34:37], off offset:16
	global_store_dwordx4 v[160:161], v[22:25], off offset:512
	global_store_dwordx4 v[160:161], v[10:13], off offset:528
	s_waitcnt vmcnt(13)
	v_pk_fma_f32 v[8:9], v[8:9], v[138:139], v[124:125]
	v_lshl_add_u64 v[22:23], v[132:133], 0, v[152:153]
	v_pk_fma_f32 v[12:13], v[20:21], v[146:147], v[116:117]
	v_pk_fma_f32 v[10:11], v[18:19], v[148:149], v[114:115]
	global_store_dwordx4 v[22:23], v[10:13], off
	v_pk_fma_f32 v[6:7], v[6:7], v[140:141], v[122:123]
	s_waitcnt vmcnt(13)
	v_pk_fma_f32 v[4:5], v[4:5], v[134:135], v[128:129]
	v_pk_fma_f32 v[12:13], v[16:17], v[142:143], v[120:121]
	v_pk_fma_f32 v[10:11], v[14:15], v[144:145], v[118:119]
	v_pk_fma_f32 v[2:3], v[2:3], v[136:137], v[126:127]
	global_store_dwordx4 v[22:23], v[10:13], off offset:16
	global_store_dwordx4 v[22:23], v[6:9], off offset:512
	global_store_dwordx4 v[22:23], v[2:5], off offset:528
	s_cbranch_vccnz .LBB0_574
	s_andn2_b64 vcc, exec, s[14:15]
	s_cbranch_vccnz .LBB0_573
	s_barrier
	s_branch .LBB0_573
	.p2align 6

; template <class Epi, bool ALIGN_EPI = PG8_ALIGN, bool SP2 = PG8_SP2>
; __device__ __forceinline__ void gemm_phase(LAS unsigned char* lds, const Gemm g, const StaticOrder& S, const Epi& E) {
;     ...
;         const bool has_next = S.next(ui + 1, nxt);
;         const char* nA = has_next ? (const char*)g.A + (size_t)nxt.pm * tstepA : cA; const char* nB = has_next ? (const char*)g.Bt + (size_t)nxt.pn * tstepB : cB;
;         for (int t = 0; t < nt; t += 2) {
;             const bool last = (t == nt - 2);
;             const char* a1 = cA + (size_t)(t + 1) * kstepA;
;             const char* a2 = last ? nA : cA + (size_t)(t + 2) * kstepA; const char* b2 = last ? nB : cB + (size_t)(t + 2) * kstepB;
;             const char* a3 = a2 + kstepA; const char* b3 = b2 + kstepB;
.LBB0_610:
	s_ashr_i32 s13, s12, 31
	s_lshl_b64 s[14:15], s[12:13], 19
	v_readlane_b32 s16, v252, 58
	v_readlane_b32 s17, v252, 59
	s_add_u32 s14, s16, s14
	s_addc_u32 s15, s17, s15
	s_and_b64 s[16:17], s[0:1], exec
	s_cselect_b32 s13, s15, s21
	s_cselect_b32 s43, s14, s20
	s_ashr_i32 s11, s10, 31
	s_lshl_b64 s[16:17], s[10:11], 19
	s_add_u32 s16, s30, s16
	s_addc_u32 s17, s31, s17
	s_and_b64 s[24:25], s[0:1], exec
	s_cselect_b32 s11, s17, s23
	s_cselect_b32 s44, s16, s22
	s_add_u32 s20, s20, 0x40080
	s_addc_u32 s21, s21, 0
	s_add_u32 s45, s22, 0x100
	s_addc_u32 s46, s23, 0
	s_mov_b32 s47, -2
	.p2align 6

; __device__ __forceinline__ unsigned cvt_pk_bf16(float lo, float hi) { const f32x2 v = {lo, hi}; return __builtin_bit_cast(unsigned, __builtin_convertvector(v, bf16v2_t)); }
; __device__ __forceinline__ float silu_f(float v) { return v * __builtin_amdgcn_rcpf(1.0f + fexp(-v)); }
;     __device__ __forceinline__ void operator()(const f32x4 (&acc)[2][2][4][2], const pg8::Unit& u, int wr, int wc, int fr, int fq) const {
;         const int row0 = u.pm * 256 + wr * 64 + fr, hc0 = u.pn * 128 + wc * 32 + 8 * fq;
; #pragma unroll
;         for (int ai = 0; ai < 2; ++ai)
; #pragma unroll
;             for (int m = 0; m < 4; ++m) { u32x4 w;
; #pragma unroll
;                 for (int n = 0; n < 2; ++n) { const f32x4 a = acc[ai][0][m][n], b = acc[ai][1][m][n];
;                     w[2 * n] = cvt_pk_bf16(silu_f(a[0]) * b[0], silu_f(a[1]) * b[1]); w[2 * n + 1] = cvt_pk_bf16(silu_f(a[2]) * b[2], silu_f(a[3]) * b[3]); }
;                 const int row = row0 + ai * 128 + m * 16;
;                 *(u32x4*)(hid + ((size_t)((row >> 8) * (DFF / 64) + (hc0 >> 6)) * 2 + ((row >> 7) & 1)) * 8192 + (row & 127) * 64 + (hc0 & 63)) = w; }
.LBB0_614:
	v_mov_b32_e32 v214, 0xbfb8aa3b
	v_mov_b32_e32 v215, 0xbfb8aa3b
	v_pk_mul_f32 v[206:207], v[126:127], v[214:215] op_sel_hi:[1,0]
	v_pk_mul_f32 v[208:209], v[128:129], v[214:215] op_sel_hi:[1,0]
	v_pk_mul_f32 v[210:211], v[118:119], v[214:215] op_sel_hi:[1,0]
	v_pk_mul_f32 v[212:213], v[120:121], v[214:215] op_sel_hi:[1,0]
	v_exp_f32_e32 v206, v206
	v_exp_f32_e32 v207, v207
	v_exp_f32_e32 v208, v208
	v_exp_f32_e32 v209, v209
	v_exp_f32_e32 v210, v210
	v_exp_f32_e32 v211, v211
	v_exp_f32_e32 v212, v212
	v_exp_f32_e32 v213, v213
	v_pk_add_f32 v[206:207], v[206:207], 1.0 op_sel_hi:[1,0]
	v_pk_add_f32 v[208:209], v[208:209], 1.0 op_sel_hi:[1,0]
	v_pk_add_f32 v[210:211], v[210:211], 1.0 op_sel_hi:[1,0]
	v_pk_add_f32 v[212:213], v[212:213], 1.0 op_sel_hi:[1,0]
	v_rcp_f32_e32 v206, v206
	v_rcp_f32_e32 v207, v207
	v_rcp_f32_e32 v208, v208
	v_rcp_f32_e32 v209, v209
	v_rcp_f32_e32 v210, v210
	v_rcp_f32_e32 v211, v211
	v_rcp_f32_e32 v212, v212
	v_rcp_f32_e32 v213, v213
	v_pk_mul_f32 v[206:207], v[126:127], v[206:207]
	v_pk_mul_f32 v[208:209], v[128:129], v[208:209]
	v_pk_mul_f32 v[210:211], v[118:119], v[210:211]
	v_pk_mul_f32 v[212:213], v[120:121], v[212:213]
	v_pk_mul_f32 v[206:207], v[206:207], v[122:123]
	v_pk_mul_f32 v[208:209], v[208:209], v[124:125]
	v_pk_mul_f32 v[210:211], v[210:211], v[114:115]
	v_pk_mul_f32 v[212:213], v[212:213], v[116:117]
	v_cvt_pk_bf16_f32 v122, v206, v207
	v_cvt_pk_bf16_f32 v123, v208, v209
	v_cvt_pk_bf16_f32 v124, v210, v211
	v_cvt_pk_bf16_f32 v125, v212, v213
	s_lshl_b32 s13, s18, 8
	s_add_i32 s13, s13, s38
	s_lshl_b32 s11, s19, 7
	s_or_b32 s11, s11, s39
	s_ashr_i32 s18, s13, 8
	s_ashr_i32 s11, s11, 6
	s_mul_i32 s18, s18, 44
	s_add_i32 s18, s18, s11
	s_ashr_i32 s19, s18, 31
	s_lshl_b64 s[18:19], s[18:19], 15
	v_readlane_b32 s20, v249, 53
	v_readlane_b32 s21, v249, 54
	s_add_u32 s18, s20, s18
	v_or_b32_e32 v143, s13, v140
	s_addc_u32 s19, s21, s19
	s_lshl_b32 s13, s13, 7
	s_and_b32 s13, s13, 0x4000
	s_add_u32 s18, s18, s13
	s_addc_u32 s19, s19, 0
	v_mov_b32_e32 v139, v1
	v_lshlrev_b32_e32 v0, 7, v143
	v_and_b32_e32 v0, 0x2780, v0
	s_andn2_b64 vcc, exec, s[0:1]
	v_lshl_add_u64 v[114:115], s[18:19], 0, v[0:1]
	v_lshl_add_u64 v[114:115], v[114:115], 0, v[138:139]
	global_store_dwordx4 v[114:115], v[122:125], off
	v_pk_mul_f32 v[206:207], v[110:111], v[214:215] op_sel_hi:[1,0]
	v_pk_mul_f32 v[208:209], v[112:113], v[214:215] op_sel_hi:[1,0]
	v_pk_mul_f32 v[210:211], v[102:103], v[214:215] op_sel_hi:[1,0]
	v_pk_mul_f32 v[212:213], v[104:105], v[214:215] op_sel_hi:[1,0]
	v_exp_f32_e32 v206, v206
	v_exp_f32_e32 v207, v207
	v_exp_f32_e32 v208, v208
	v_exp_f32_e32 v209, v209
	v_exp_f32_e32 v210, v210
	v_exp_f32_e32 v211, v211
	v_exp_f32_e32 v212, v212
	v_exp_f32_e32 v213, v213
	v_pk_add_f32 v[206:207], v[206:207], 1.0 op_sel_hi:[1,0]
	v_pk_add_f32 v[208:209], v[208:209], 1.0 op_sel_hi:[1,0]
	v_pk_add_f32 v[210:211], v[210:211], 1.0 op_sel_hi:[1,0]
	v_pk_add_f32 v[212:213], v[212:213], 1.0 op_sel_hi:[1,0]
	v_rcp_f32_e32 v206, v206
	v_rcp_f32_e32 v207, v207
	v_rcp_f32_e32 v208, v208
	v_rcp_f32_e32 v209, v209
	v_rcp_f32_e32 v210, v210
	v_rcp_f32_e32 v211, v211
	v_rcp_f32_e32 v212, v212
	v_rcp_f32_e32 v213, v213
	v_pk_mul_f32 v[206:207], v[110:111], v[206:207]
	v_pk_mul_f32 v[208:209], v[112:113], v[208:209]
	v_pk_mul_f32 v[210:211], v[102:103], v[210:211]
	v_pk_mul_f32 v[212:213], v[104:105], v[212:213]
	v_pk_mul_f32 v[206:207], v[206:207], v[106:107]
	v_pk_mul_f32 v[208:209], v[208:209], v[108:109]
	v_pk_mul_f32 v[210:211], v[210:211], v[98:99]
	v_pk_mul_f32 v[212:213], v[212:213], v[100:101]
	v_cvt_pk_bf16_f32 v106, v206, v207
	v_cvt_pk_bf16_f32 v107, v208, v209
	v_cvt_pk_bf16_f32 v108, v210, v211
	v_cvt_pk_bf16_f32 v109, v212, v213
	global_store_dwordx4 v[114:115], v[106:109], off offset:2048
	v_pk_mul_f32 v[206:207], v[94:95], v[214:215] op_sel_hi:[1,0]
	v_pk_mul_f32 v[208:209], v[96:97], v[214:215] op_sel_hi:[1,0]
	v_pk_mul_f32 v[210:211], v[86:87], v[214:215] op_sel_hi:[1,0]
	v_pk_mul_f32 v[212:213], v[88:89], v[214:215] op_sel_hi:[1,0]
	v_exp_f32_e32 v206, v206
	v_exp_f32_e32 v207, v207
	v_exp_f32_e32 v208, v208
	v_exp_f32_e32 v209, v209
	v_exp_f32_e32 v210, v210
	v_exp_f32_e32 v211, v211
	v_exp_f32_e32 v212, v212
	v_exp_f32_e32 v213, v213
	v_pk_add_f32 v[206:207], v[206:207], 1.0 op_sel_hi:[1,0]
	v_pk_add_f32 v[208:209], v[208:209], 1.0 op_sel_hi:[1,0]
	v_pk_add_f32 v[210:211], v[210:211], 1.0 op_sel_hi:[1,0]
	v_pk_add_f32 v[212:213], v[212:213], 1.0 op_sel_hi:[1,0]
	v_rcp_f32_e32 v206, v206
	v_rcp_f32_e32 v207, v207
	v_rcp_f32_e32 v208, v208
	v_rcp_f32_e32 v209, v209
	v_rcp_f32_e32 v210, v210
	v_rcp_f32_e32 v211, v211
	v_rcp_f32_e32 v212, v212
	v_rcp_f32_e32 v213, v213
	v_pk_mul_f32 v[206:207], v[94:95], v[206:207]
	v_pk_mul_f32 v[208:209], v[96:97], v[208:209]
	v_pk_mul_f32 v[210:211], v[86:87], v[210:211]
	v_pk_mul_f32 v[212:213], v[88:89], v[212:213]
	v_pk_mul_f32 v[206:207], v[206:207], v[90:91]
	v_pk_mul_f32 v[208:209], v[208:209], v[92:93]
	v_pk_mul_f32 v[210:211], v[210:211], v[82:83]
	v_pk_mul_f32 v[212:213], v[212:213], v[84:85]
	v_cvt_pk_bf16_f32 v90, v206, v207
	v_cvt_pk_bf16_f32 v91, v208, v209
	v_cvt_pk_bf16_f32 v92, v210, v211
	v_cvt_pk_bf16_f32 v93, v212, v213
	v_or_b32_e32 v82, 0x1000, v0
	v_mov_b32_e32 v83, v1
	v_lshl_add_u64 v[84:85], s[18:19], 0, v[82:83]
	v_lshl_add_u64 v[84:85], v[84:85], 0, v[138:139]
	global_store_dwordx4 v[84:85], v[90:93], off
	v_pk_mul_f32 v[206:207], v[78:79], v[214:215] op_sel_hi:[1,0]
	v_pk_mul_f32 v[208:209], v[80:81], v[214:215] op_sel_hi:[1,0]
	v_pk_mul_f32 v[210:211], v[70:71], v[214:215] op_sel_hi:[1,0]
	v_pk_mul_f32 v[212:213], v[72:73], v[214:215] op_sel_hi:[1,0]
; __device__ __forceinline__ unsigned cvt_pk_bf16(float lo, float hi) { const f32x2 v = {lo, hi}; return __builtin_bit_cast(unsigned, __builtin_convertvector(v, bf16v2_t)); }
; __device__ __forceinline__ float silu_f(float v) { return v * __builtin_amdgcn_rcpf(1.0f + fexp(-v)); }
;     __device__ __forceinline__ void operator()(const f32x4 (&acc)[2][2][4][2], const pg8::Unit& u, int wr, int wc, int fr, int fq) const {
;     ...
;         for (int ai = 0; ai < 2; ++ai)
; #pragma unroll
;             for (int m = 0; m < 4; ++m) { u32x4 w;
; #pragma unroll
;                 for (int n = 0; n < 2; ++n) { const f32x4 a = acc[ai][0][m][n], b = acc[ai][1][m][n];
;                     w[2 * n] = cvt_pk_bf16(silu_f(a[0]) * b[0], silu_f(a[1]) * b[1]); w[2 * n + 1] = cvt_pk_bf16(silu_f(a[2]) * b[2], silu_f(a[3]) * b[3]); }
;                 const int row = row0 + ai * 128 + m * 16;
;                 *(u32x4*)(hid + ((size_t)((row >> 8) * (DFF / 64) + (hc0 >> 6)) * 2 + ((row >> 7) & 1)) * 8192 + (row & 127) * 64 + (hc0 & 63)) = w; }
	v_exp_f32_e32 v206, v206
	v_exp_f32_e32 v207, v207
	v_exp_f32_e32 v208, v208
	v_exp_f32_e32 v209, v209
	v_exp_f32_e32 v210, v210
	v_exp_f32_e32 v211, v211
	v_exp_f32_e32 v212, v212
	v_exp_f32_e32 v213, v213
	v_pk_add_f32 v[206:207], v[206:207], 1.0 op_sel_hi:[1,0]
	v_pk_add_f32 v[208:209], v[208:209], 1.0 op_sel_hi:[1,0]
	v_pk_add_f32 v[210:211], v[210:211], 1.0 op_sel_hi:[1,0]
	v_pk_add_f32 v[212:213], v[212:213], 1.0 op_sel_hi:[1,0]
	v_rcp_f32_e32 v206, v206
	v_rcp_f32_e32 v207, v207
	v_rcp_f32_e32 v208, v208
	v_rcp_f32_e32 v209, v209
	v_rcp_f32_e32 v210, v210
	v_rcp_f32_e32 v211, v211
	v_rcp_f32_e32 v212, v212
	v_rcp_f32_e32 v213, v213
	v_pk_mul_f32 v[206:207], v[78:79], v[206:207]
	v_pk_mul_f32 v[208:209], v[80:81], v[208:209]
	v_pk_mul_f32 v[210:211], v[70:71], v[210:211]
	v_pk_mul_f32 v[212:213], v[72:73], v[212:213]
	v_pk_mul_f32 v[206:207], v[206:207], v[74:75]
	v_pk_mul_f32 v[208:209], v[208:209], v[76:77]
	v_pk_mul_f32 v[210:211], v[210:211], v[66:67]
	v_pk_mul_f32 v[212:213], v[212:213], v[68:69]
	v_cvt_pk_bf16_f32 v74, v206, v207
	v_cvt_pk_bf16_f32 v75, v208, v209
	v_cvt_pk_bf16_f32 v76, v210, v211
	v_cvt_pk_bf16_f32 v77, v212, v213
	v_add_u32_e32 v72, 0x80, v143
	v_or_b32_e32 v66, 0x1800, v0
	v_mov_b32_e32 v67, v1
	v_lshl_add_u64 v[68:69], s[18:19], 0, v[66:67]
	v_lshl_add_u64 v[68:69], v[68:69], 0, v[138:139]
	global_store_dwordx4 v[68:69], v[74:77], off
	v_pk_mul_f32 v[206:207], v[62:63], v[214:215] op_sel_hi:[1,0]
	v_pk_mul_f32 v[208:209], v[64:65], v[214:215] op_sel_hi:[1,0]
	v_pk_mul_f32 v[210:211], v[54:55], v[214:215] op_sel_hi:[1,0]
	v_pk_mul_f32 v[212:213], v[56:57], v[214:215] op_sel_hi:[1,0]
	v_exp_f32_e32 v206, v206
	v_exp_f32_e32 v207, v207
	v_exp_f32_e32 v208, v208
	v_exp_f32_e32 v209, v209
	v_exp_f32_e32 v210, v210
	v_exp_f32_e32 v211, v211
	v_exp_f32_e32 v212, v212
	v_exp_f32_e32 v213, v213
	v_pk_add_f32 v[206:207], v[206:207], 1.0 op_sel_hi:[1,0]
	v_pk_add_f32 v[208:209], v[208:209], 1.0 op_sel_hi:[1,0]
	v_pk_add_f32 v[210:211], v[210:211], 1.0 op_sel_hi:[1,0]
	v_pk_add_f32 v[212:213], v[212:213], 1.0 op_sel_hi:[1,0]
	v_rcp_f32_e32 v206, v206
	v_rcp_f32_e32 v207, v207
	v_rcp_f32_e32 v208, v208
	v_rcp_f32_e32 v209, v209
	v_rcp_f32_e32 v210, v210
	v_rcp_f32_e32 v211, v211
	v_rcp_f32_e32 v212, v212
	v_rcp_f32_e32 v213, v213
	v_pk_mul_f32 v[206:207], v[62:63], v[206:207]
	v_pk_mul_f32 v[208:209], v[64:65], v[208:209]
	v_pk_mul_f32 v[210:211], v[54:55], v[210:211]
	v_pk_mul_f32 v[212:213], v[56:57], v[212:213]
	v_pk_mul_f32 v[206:207], v[206:207], v[58:59]
	v_pk_mul_f32 v[208:209], v[208:209], v[60:61]
	v_pk_mul_f32 v[210:211], v[210:211], v[50:51]
	v_pk_mul_f32 v[212:213], v[212:213], v[52:53]
	v_cvt_pk_bf16_f32 v58, v206, v207
	v_cvt_pk_bf16_f32 v59, v208, v209
	v_cvt_pk_bf16_f32 v60, v210, v211
	v_cvt_pk_bf16_f32 v61, v212, v213
	v_lshrrev_b32_e32 v68, 8, v72
	v_mad_i32_i24 v68, v68, 44, s11
	v_ashrrev_i32_e32 v69, 31, v68
	v_lshlrev_b64 v[68:69], 15, v[68:69]
	s_mov_b64 s[18:19], -1
	v_lshlrev_b32_e32 v52, 7, v72
	v_lshl_add_u64 v[50:51], s[20:21], 0, v[68:69]
	v_and_b32_e32 v52, 0x4000, v52
	v_mov_b32_e32 v53, v1
	v_lshl_add_u64 v[50:51], v[50:51], 0, v[52:53]
	v_lshl_add_u64 v[52:53], v[50:51], 0, v[0:1]
	v_lshl_add_u64 v[52:53], v[52:53], 0, v[138:139]
	global_store_dwordx4 v[52:53], v[58:61], off
	v_pk_mul_f32 v[206:207], v[46:47], v[214:215] op_sel_hi:[1,0]
	v_pk_mul_f32 v[208:209], v[48:49], v[214:215] op_sel_hi:[1,0]
	v_pk_mul_f32 v[210:211], v[38:39], v[214:215] op_sel_hi:[1,0]
	v_pk_mul_f32 v[212:213], v[40:41], v[214:215] op_sel_hi:[1,0]
	v_exp_f32_e32 v206, v206
	v_exp_f32_e32 v207, v207
	v_exp_f32_e32 v208, v208
	v_exp_f32_e32 v209, v209
	v_exp_f32_e32 v210, v210
	v_exp_f32_e32 v211, v211
	v_exp_f32_e32 v212, v212
	v_exp_f32_e32 v213, v213
	v_pk_add_f32 v[206:207], v[206:207], 1.0 op_sel_hi:[1,0]
	v_pk_add_f32 v[208:209], v[208:209], 1.0 op_sel_hi:[1,0]
	v_pk_add_f32 v[210:211], v[210:211], 1.0 op_sel_hi:[1,0]
	v_pk_add_f32 v[212:213], v[212:213], 1.0 op_sel_hi:[1,0]
	v_rcp_f32_e32 v206, v206
; __device__ __forceinline__ unsigned cvt_pk_bf16(float lo, float hi) { const f32x2 v = {lo, hi}; return __builtin_bit_cast(unsigned, __builtin_convertvector(v, bf16v2_t)); }
; __device__ __forceinline__ float silu_f(float v) { return v * __builtin_amdgcn_rcpf(1.0f + fexp(-v)); }
; #define PG8_BAR __builtin_amdgcn_s_barrier()
; template <class Epi, bool ALIGN_EPI = PG8_ALIGN, bool SP2 = PG8_SP2>
; __device__ __forceinline__ void gemm_phase(LAS unsigned char* lds, const Gemm g, const StaticOrder& S, const Epi& E) {
;     ...
;         if (!has_next) break;
; #pragma unroll
;         for (int a = 0; a < 2; ++a)
; #pragma unroll
;             for (int b = 0; b < 2; ++b)
; #pragma unroll
;                 for (int m = 0; m < 4; ++m)
; #pragma unroll
;                     for (int n = 0; n < 2; ++n) acc[a][b][m][n] = (f32x4){0.f, 0.f, 0.f, 0.f};
;         cur = nxt; cA = nA; cB = nB; ++ui;
;         if constexpr (ALIGN_EPI) { if (wr == 1) PG8_BAR; }
;     __device__ __forceinline__ void operator()(const f32x4 (&acc)[2][2][4][2], const pg8::Unit& u, int wr, int wc, int fr, int fq) const {
;     ...
;         for (int ai = 0; ai < 2; ++ai)
; #pragma unroll
;             for (int m = 0; m < 4; ++m) { u32x4 w;
; #pragma unroll
;                 for (int n = 0; n < 2; ++n) { const f32x4 a = acc[ai][0][m][n], b = acc[ai][1][m][n];
;                     w[2 * n] = cvt_pk_bf16(silu_f(a[0]) * b[0], silu_f(a[1]) * b[1]); w[2 * n + 1] = cvt_pk_bf16(silu_f(a[2]) * b[2], silu_f(a[3]) * b[3]); }
;                 const int row = row0 + ai * 128 + m * 16;
;                 *(u32x4*)(hid + ((size_t)((row >> 8) * (DFF / 64) + (hc0 >> 6)) * 2 + ((row >> 7) & 1)) * 8192 + (row & 127) * 64 + (hc0 & 63)) = w; }
	v_rcp_f32_e32 v207, v207
	v_rcp_f32_e32 v208, v208
	v_rcp_f32_e32 v209, v209
	v_rcp_f32_e32 v210, v210
	v_rcp_f32_e32 v211, v211
	v_rcp_f32_e32 v212, v212
	v_rcp_f32_e32 v213, v213
	v_pk_mul_f32 v[206:207], v[46:47], v[206:207]
	v_pk_mul_f32 v[208:209], v[48:49], v[208:209]
	v_pk_mul_f32 v[210:211], v[38:39], v[210:211]
	v_pk_mul_f32 v[212:213], v[40:41], v[212:213]
	v_pk_mul_f32 v[206:207], v[206:207], v[42:43]
	v_pk_mul_f32 v[208:209], v[208:209], v[44:45]
	v_pk_mul_f32 v[210:211], v[210:211], v[34:35]
	v_pk_mul_f32 v[212:213], v[212:213], v[36:37]
	v_cvt_pk_bf16_f32 v42, v206, v207
	v_cvt_pk_bf16_f32 v43, v208, v209
	v_cvt_pk_bf16_f32 v44, v210, v211
	v_cvt_pk_bf16_f32 v45, v212, v213
	global_store_dwordx4 v[52:53], v[42:45], off offset:2048
	v_pk_mul_f32 v[206:207], v[30:31], v[214:215] op_sel_hi:[1,0]
	v_pk_mul_f32 v[208:209], v[32:33], v[214:215] op_sel_hi:[1,0]
	v_pk_mul_f32 v[210:211], v[22:23], v[214:215] op_sel_hi:[1,0]
	v_pk_mul_f32 v[212:213], v[24:25], v[214:215] op_sel_hi:[1,0]
	v_exp_f32_e32 v206, v206
	v_exp_f32_e32 v207, v207
	v_exp_f32_e32 v208, v208
	v_exp_f32_e32 v209, v209
	v_exp_f32_e32 v210, v210
	v_exp_f32_e32 v211, v211
	v_exp_f32_e32 v212, v212
	v_exp_f32_e32 v213, v213
	v_pk_add_f32 v[206:207], v[206:207], 1.0 op_sel_hi:[1,0]
	v_pk_add_f32 v[208:209], v[208:209], 1.0 op_sel_hi:[1,0]
	v_pk_add_f32 v[210:211], v[210:211], 1.0 op_sel_hi:[1,0]
	v_pk_add_f32 v[212:213], v[212:213], 1.0 op_sel_hi:[1,0]
	v_rcp_f32_e32 v206, v206
	v_rcp_f32_e32 v207, v207
	v_rcp_f32_e32 v208, v208
	v_rcp_f32_e32 v209, v209
	v_rcp_f32_e32 v210, v210
	v_rcp_f32_e32 v211, v211
	v_rcp_f32_e32 v212, v212
	v_rcp_f32_e32 v213, v213
	v_pk_mul_f32 v[206:207], v[30:31], v[206:207]
	v_pk_mul_f32 v[208:209], v[32:33], v[208:209]
	v_pk_mul_f32 v[210:211], v[22:23], v[210:211]
	v_pk_mul_f32 v[212:213], v[24:25], v[212:213]
	v_pk_mul_f32 v[206:207], v[206:207], v[26:27]
	v_pk_mul_f32 v[208:209], v[208:209], v[28:29]
	v_pk_mul_f32 v[210:211], v[210:211], v[18:19]
	v_pk_mul_f32 v[212:213], v[212:213], v[20:21]
	v_cvt_pk_bf16_f32 v26, v206, v207
	v_cvt_pk_bf16_f32 v27, v208, v209
	v_cvt_pk_bf16_f32 v28, v210, v211
	v_cvt_pk_bf16_f32 v29, v212, v213
	v_lshl_add_u64 v[18:19], v[50:51], 0, v[82:83]
	v_lshl_add_u64 v[18:19], v[18:19], 0, v[138:139]
	global_store_dwordx4 v[18:19], v[26:29], off
	v_pk_mul_f32 v[206:207], v[14:15], v[214:215] op_sel_hi:[1,0]
	v_pk_mul_f32 v[208:209], v[16:17], v[214:215] op_sel_hi:[1,0]
	v_pk_mul_f32 v[210:211], v[6:7], v[214:215] op_sel_hi:[1,0]
	v_pk_mul_f32 v[212:213], v[8:9], v[214:215] op_sel_hi:[1,0]
	v_exp_f32_e32 v206, v206
	v_exp_f32_e32 v207, v207
	v_exp_f32_e32 v208, v208
	v_exp_f32_e32 v209, v209
	v_exp_f32_e32 v210, v210
	v_exp_f32_e32 v211, v211
	v_exp_f32_e32 v212, v212
	v_exp_f32_e32 v213, v213
	v_pk_add_f32 v[206:207], v[206:207], 1.0 op_sel_hi:[1,0]
	v_pk_add_f32 v[208:209], v[208:209], 1.0 op_sel_hi:[1,0]
	v_pk_add_f32 v[210:211], v[210:211], 1.0 op_sel_hi:[1,0]
	v_pk_add_f32 v[212:213], v[212:213], 1.0 op_sel_hi:[1,0]
	v_rcp_f32_e32 v206, v206
	v_rcp_f32_e32 v207, v207
	v_rcp_f32_e32 v208, v208
	v_rcp_f32_e32 v209, v209
	v_rcp_f32_e32 v210, v210
	v_rcp_f32_e32 v211, v211
	v_rcp_f32_e32 v212, v212
	v_rcp_f32_e32 v213, v213
	v_pk_mul_f32 v[206:207], v[14:15], v[206:207]
	v_pk_mul_f32 v[208:209], v[16:17], v[208:209]
	v_pk_mul_f32 v[210:211], v[6:7], v[210:211]
	v_pk_mul_f32 v[212:213], v[8:9], v[212:213]
	v_pk_mul_f32 v[206:207], v[206:207], v[10:11]
	v_pk_mul_f32 v[208:209], v[208:209], v[12:13]
	v_pk_mul_f32 v[210:211], v[210:211], v[2:3]
	v_pk_mul_f32 v[212:213], v[212:213], v[4:5]
	v_cvt_pk_bf16_f32 v10, v206, v207
	v_cvt_pk_bf16_f32 v11, v208, v209
	v_cvt_pk_bf16_f32 v12, v210, v211
	v_cvt_pk_bf16_f32 v13, v212, v213
	v_lshl_add_u64 v[2:3], v[50:51], 0, v[66:67]
	v_lshl_add_u64 v[2:3], v[2:3], 0, v[138:139]
	global_store_dwordx4 v[2:3], v[10:13], off
	s_cbranch_vccnz .LBB0_603
	s_andn2_b64 vcc, exec, s[6:7]
	s_cbranch_vccnz .LBB0_602
	s_barrier
	s_branch .LBB0_602
	.p2align 6
